# P5 step B head: counted waits (vmcnt 9 at the head, 4 and 0 where the early vT fragments are moved into place) instead of the vmcnt(0) drain
# speedup vs baseline: 1.0031x; 1.0018x over previous
.LBB0_456:
	v_bfe_u32 v138, v170, 4, 2
	v_lshl_add_u32 v139, v169, 8, 0
	v_xor_b32_e32 v2, v138, v169
	s_lshl_b32 s6, s74, 3
	v_lshl_add_u32 v98, v2, 4, v139
	s_ashr_i32 s7, s6, 31
	s_waitcnt lgkmcnt(0)
	s_barrier
	ds_read_b128 v[2:5], v98
	ds_read_b128 v[10:13], v98 offset:4096
	ds_read_b128 v[90:93], v98 offset:8192
	ds_read_b128 v[98:101], v98 offset:12288
	s_lshl_b64 s[6:7], s[6:7], 11
	s_lshl_b32 s73, s73, 9
	s_add_u32 s8, s73, s31
	s_addc_u32 s9, 0, s46
	s_add_u32 s6, s8, s6
	s_addc_u32 s7, s9, s7
	s_waitcnt lgkmcnt(3)
	s_waitcnt vmcnt(9)
	v_mfma_f32_16x16x32_bf16 v[6:9], v[192:195], v[2:5], 0
	v_mov_b32_e32 v123, s7
	v_or_b32_e32 v122, s6, v169
	v_lshlrev_b32_e32 v124, 3, v138
	s_waitcnt lgkmcnt(2)
	v_mfma_f32_16x16x32_bf16 v[14:17], v[192:195], v[10:13], 0
	v_lshlrev_b64 v[122:123], 6, v[122:123]
	v_lshl_add_u64 v[122:123], s[20:21], 0, v[122:123]
	v_lshlrev_b32_e32 v124, 1, v124
	s_waitcnt lgkmcnt(1)
	v_mfma_f32_16x16x32_bf16 v[94:97], v[192:195], v[90:93], 0
	v_mov_b32_e32 v125, v163
	v_lshl_add_u64 v[166:167], v[122:123], 0, v[124:125]
	s_waitcnt lgkmcnt(0)
	v_mfma_f32_16x16x32_bf16 v[66:69], v[192:195], v[98:101], 0
	v_mfma_f32_16x16x32_bf16 v[102:105], v[248:251], v[2:5], 0
	v_mfma_f32_16x16x32_bf16 v[106:109], v[248:251], v[10:13], 0
	v_mfma_f32_16x16x32_bf16 v[110:113], v[248:251], v[90:93], 0
	v_mfma_f32_16x16x32_bf16 v[86:89], v[248:251], v[98:101], 0
	v_mfma_f32_16x16x32_bf16 v[114:117], v[200:203], v[2:5], 0
	v_mfma_f32_16x16x32_bf16 v[118:121], v[200:203], v[10:13], 0
	v_mfma_f32_16x16x32_bf16 v[140:143], v[200:203], v[90:93], 0
	v_mfma_f32_16x16x32_bf16 v[46:49], v[200:203], v[98:101], 0
	v_mfma_f32_16x16x32_bf16 v[2:5], v[232:235], v[2:5], 0
	v_mfma_f32_16x16x32_bf16 v[10:13], v[232:235], v[10:13], 0
	v_mfma_f32_16x16x32_bf16 v[90:93], v[232:235], v[90:93], 0
	v_mfma_f32_16x16x32_bf16 v[42:45], v[232:235], v[98:101], 0
	s_waitcnt vmcnt(4)
	v_mov_b32_e32 v122, v54
	v_mov_b32_e32 v123, v55
	v_mov_b32_e32 v124, v56
	v_mov_b32_e32 v125, v57
	v_bitop3_b32 v98, v138, v169, 4 bitop3:0x36
	v_lshl_add_u32 v152, v98, 4, v139
	ds_read_b128 v[98:101], v152
	ds_read_b128 v[144:147], v152 offset:4096
	ds_read_b128 v[148:151], v152 offset:8192
	ds_read_b128 v[152:155], v152 offset:12288
	s_waitcnt lgkmcnt(3)
	v_mfma_f32_16x16x32_bf16 v[6:9], v[196:199], v[98:101], v[6:9]
	s_waitcnt lgkmcnt(2)
	v_mfma_f32_16x16x32_bf16 v[14:17], v[196:199], v[144:147], v[14:17]
	s_waitcnt lgkmcnt(1)
	v_mfma_f32_16x16x32_bf16 v[94:97], v[196:199], v[148:151], v[94:97]
	s_waitcnt lgkmcnt(0)
	v_mfma_f32_16x16x32_bf16 v[34:37], v[196:199], v[152:155], v[66:69]
	v_mfma_f32_16x16x32_bf16 v[66:69], v[208:211], v[98:101], v[102:105]
	v_mfma_f32_16x16x32_bf16 v[102:105], v[208:211], v[144:147], v[106:109]
	v_mfma_f32_16x16x32_bf16 v[156:159], v[208:211], v[148:151], v[110:113]
	v_mfma_f32_16x16x32_bf16 v[38:41], v[208:211], v[152:155], v[86:89]
	v_mfma_f32_16x16x32_bf16 v[86:89], v[204:207], v[98:101], v[114:117]
	v_mfma_f32_16x16x32_bf16 v[98:101], v[216:219], v[98:101], v[2:5]
	v_mfma_f32_16x16x32_bf16 v[172:175], v[204:207], v[144:147], v[118:121]
	v_mfma_f32_16x16x32_bf16 v[140:143], v[204:207], v[148:151], v[140:143]
	v_mfma_f32_16x16x32_bf16 v[176:179], v[204:207], v[152:155], v[46:49]
	v_mfma_f32_16x16x32_bf16 v[144:147], v[216:219], v[144:147], v[10:13]
	v_mfma_f32_16x16x32_bf16 v[148:151], v[216:219], v[148:151], v[90:93]
	v_mfma_f32_16x16x32_bf16 v[152:155], v[216:219], v[152:155], v[42:45]
	v_add_co_u32_e32 v2, vcc, s69, v166
	s_nop 1
	v_addc_co_u32_e32 v3, vcc, 0, v167, vcc
	s_waitcnt vmcnt(0)
	v_mov_b32_e32 v118, v70
	v_mov_b32_e32 v119, v71
	v_mov_b32_e32 v120, v72
	v_mov_b32_e32 v121, v73
	v_mov_b32_e32 v114, v74
	v_mov_b32_e32 v115, v75
	v_mov_b32_e32 v116, v76
	v_mov_b32_e32 v117, v77
	v_mov_b32_e32 v110, v78
	v_mov_b32_e32 v111, v79
	v_mov_b32_e32 v112, v80
	v_mov_b32_e32 v113, v81
	v_mov_b32_e32 v106, v82
	v_mov_b32_e32 v107, v83
	v_mov_b32_e32 v108, v84
	v_mov_b32_e32 v109, v85
	v_bitop3_b32 v2, v138, v169, 8 bitop3:0x36
	v_lshl_add_u32 v26, v2, 4, v139
	ds_read_b128 v[90:93], v26
	ds_read_b128 v[180:183], v26 offset:4096
	ds_read_b128 v[184:187], v26 offset:8192
	ds_read_b128 v[188:191], v26 offset:12288
	s_waitcnt lgkmcnt(3)
	v_mfma_f32_16x16x32_bf16 v[2:5], v[224:227], v[90:93], v[6:9]
	s_waitcnt lgkmcnt(2)
	v_mfma_f32_16x16x32_bf16 v[6:9], v[224:227], v[180:183], v[14:17]
	s_waitcnt lgkmcnt(1)
	v_mfma_f32_16x16x32_bf16 v[10:13], v[224:227], v[184:187], v[94:97]
	s_waitcnt lgkmcnt(0)
	v_mfma_f32_16x16x32_bf16 v[14:17], v[224:227], v[188:191], v[34:37]
	v_mfma_f32_16x16x32_bf16 v[26:29], v[212:215], v[90:93], v[66:69]
	v_mfma_f32_16x16x32_bf16 v[30:33], v[212:215], v[180:183], v[102:105]
	v_mfma_f32_16x16x32_bf16 v[34:37], v[212:215], v[184:187], v[156:159]
	v_mfma_f32_16x16x32_bf16 v[38:41], v[212:215], v[188:191], v[38:41]
	v_mfma_f32_16x16x32_bf16 v[42:45], v[240:243], v[90:93], v[86:89]
	v_mfma_f32_16x16x32_bf16 v[46:49], v[240:243], v[180:183], v[172:175]
	v_mfma_f32_16x16x32_bf16 v[66:69], v[240:243], v[184:187], v[140:143]
	v_mfma_f32_16x16x32_bf16 v[86:89], v[240:243], v[188:191], v[176:179]
	v_mfma_f32_16x16x32_bf16 v[90:93], v[220:223], v[90:93], v[98:101]
	v_mfma_f32_16x16x32_bf16 v[94:97], v[220:223], v[180:183], v[144:147]
	v_mfma_f32_16x16x32_bf16 v[98:101], v[220:223], v[184:187], v[148:151]
	v_mfma_f32_16x16x32_bf16 v[102:105], v[220:223], v[188:191], v[152:155]
	s_cmp_lg_u32 s75, 0
	s_cselect_b64 s[6:7], -1, 0
	s_cmp_eq_u32 s75, 0
	s_cbranch_scc1 .LBB0_458
	v_add_co_u32_e32 v70, vcc, 0x40000, v166
	s_nop 1
	v_addc_co_u32_e32 v71, vcc, 0, v167, vcc
	global_load_dwordx4 v[82:85], v[70:71], off
	global_load_dwordx4 v[74:77], v[70:71], off offset:1024
	global_load_dwordx4 v[78:81], v[70:71], off offset:2048
	s_nop 0
	global_load_dwordx4 v[70:73], v[70:71], off offset:3072
